# P4 LayerNorm partial statistics of row groups 1..7 with packed f32 math (v_pk_add tree, v_pk_fma deviations and square accumulation): 38 instead of about 70 VALU per group, same two-pass f32 algorithm
# baseline (speedup 1.0000x reference)
.LBB0_391:
	s_mov_b32 s96, 0xbc800000
	s_mov_b32 s97, 0xbc800000
	s_lshl_b32 s39, s14, 8
	v_add_u32_e32 v176, s39, v180
	v_lshl_or_b32 v128, s46, 8, v182
	v_ashrrev_i32_e32 v177, 31, v176
	v_ashrrev_i32_e32 v129, 31, v128
	v_lshlrev_b64 v[130:131], 11, v[176:177]
	v_lshl_add_u64 v[132:133], s[16:17], 0, v[130:131]
	v_lshlrev_b64 v[130:131], 1, v[128:129]
	v_lshl_add_u64 v[132:133], v[132:133], 0, v[130:131]
	s_mov_b64 s[80:81], 0x8000
	s_mov_b64 s[82:83], 0x28000
	v_lshrrev_b32_e32 v252, 4, v203
	v_lshlrev_b32_e32 v252, 3, v252
	v_mov_b32_e32 v253, 0
	v_lshl_add_u64 v[254:255], v[132:133], 0, v[252:253]
	global_load_dwordx4 v[210:213], v[254:255], off nt
	global_load_dwordx4 v[214:217], v[254:255], off offset:256 nt
	v_lshl_add_u64 v[254:255], v[254:255], 0, s[80:81]
	global_load_dwordx4 v[218:221], v[254:255], off nt
	global_load_dwordx4 v[222:225], v[254:255], off offset:256 nt
	v_lshl_add_u64 v[254:255], v[254:255], 0, s[80:81]
	global_load_dwordx4 v[226:229], v[254:255], off nt
	global_load_dwordx4 v[230:233], v[254:255], off offset:256 nt
	v_lshl_add_u64 v[254:255], v[254:255], 0, s[80:81]
	global_load_dwordx4 v[234:237], v[254:255], off nt
	global_load_dwordx4 v[238:241], v[254:255], off offset:256 nt
	v_lshl_add_u64 v[254:255], v[254:255], 0, s[82:83]
	global_load_dwordx4 v[242:245], v[254:255], off nt
	global_load_dwordx4 v[246:249], v[254:255], off offset:256 nt
	v_lshl_add_u64 v[254:255], v[254:255], 0, s[80:81]
	v_or_b32_e32 v140, 16, v176
	v_ashrrev_i32_e32 v141, 31, v140
	v_lshlrev_b64 v[140:141], 11, v[140:141]
	v_lshl_add_u64 v[140:141], s[16:17], 0, v[140:141]
	v_lshl_add_u64 v[140:141], v[140:141], 0, v[130:131]
	s_waitcnt vmcnt(8)
	v_permlane16_swap_b32_e32 v210, v212
	v_permlane16_swap_b32_e32 v211, v213
	v_permlane16_swap_b32_e32 v214, v216
	v_permlane16_swap_b32_e32 v215, v217
	v_permlane32_swap_b32_e32 v210, v212
	v_permlane32_swap_b32_e32 v211, v213
	v_permlane32_swap_b32_e32 v214, v216
	v_permlane32_swap_b32_e32 v215, v217
	v_mov_b32_e32 v134, v210
	v_mov_b32_e32 v135, v211
	v_mov_b32_e32 v136, v212
	v_mov_b32_e32 v137, v213
	v_mov_b32_e32 v138, v214
	v_mov_b32_e32 v139, v215
	v_mov_b32_e32 v132, v216
	v_mov_b32_e32 v133, v217
	global_load_dwordx4 v[210:213], v[254:255], off nt
	global_load_dwordx4 v[214:217], v[254:255], off offset:256 nt
	v_lshl_add_u64 v[254:255], v[254:255], 0, s[80:81]
	v_lshlrev_b32_e32 v142, 16, v134
	v_and_b32_e32 v143, 0xffff0000, v134
	v_lshlrev_b32_e32 v134, 16, v135
	v_and_b32_e32 v135, 0xffff0000, v135
	v_lshlrev_b32_e32 v144, 16, v136
	v_and_b32_e32 v145, 0xffff0000, v136
	v_lshlrev_b32_e32 v136, 16, v137
	v_and_b32_e32 v137, 0xffff0000, v137
	v_lshlrev_b32_e32 v146, 16, v138
	v_and_b32_e32 v147, 0xffff0000, v138
	v_lshlrev_b32_e32 v138, 16, v139
	v_and_b32_e32 v139, 0xffff0000, v139
	v_lshlrev_b32_e32 v148, 16, v132
	v_and_b32_e32 v149, 0xffff0000, v132
	v_lshlrev_b32_e32 v132, 16, v133
	v_and_b32_e32 v133, 0xffff0000, v133
	v_pk_fma_f32 v[46:47], v[134:135], s[36:37], v[46:47] op_sel_hi:[1,0,1]
	v_pk_fma_f32 v[44:45], v[142:143], s[36:37], v[44:45] op_sel_hi:[1,0,1]
	v_pk_fma_f32 v[42:43], v[136:137], s[36:37], v[42:43] op_sel_hi:[1,0,1]
	v_pk_fma_f32 v[40:41], v[144:145], s[36:37], v[40:41] op_sel_hi:[1,0,1]
	v_pk_fma_f32 v[38:39], v[138:139], s[36:37], v[38:39] op_sel_hi:[1,0,1]
	v_pk_fma_f32 v[36:37], v[146:147], s[36:37], v[36:37] op_sel_hi:[1,0,1]
	v_pk_fma_f32 v[34:35], v[132:133], s[36:37], v[34:35] op_sel_hi:[1,0,1]
	v_pk_fma_f32 v[32:33], v[148:149], s[36:37], v[32:33] op_sel_hi:[1,0,1]
	s_nop 0
	s_waitcnt vmcnt(8)
	v_permlane16_swap_b32_e32 v218, v220
	v_permlane16_swap_b32_e32 v219, v221
	v_permlane16_swap_b32_e32 v222, v224
	v_permlane16_swap_b32_e32 v223, v225
	v_permlane32_swap_b32_e32 v218, v220
	v_permlane32_swap_b32_e32 v219, v221
	v_permlane32_swap_b32_e32 v222, v224
	v_permlane32_swap_b32_e32 v223, v225
	v_mov_b32_e32 v132, v218
	v_mov_b32_e32 v133, v219
	v_mov_b32_e32 v134, v220
	v_mov_b32_e32 v135, v221
	v_mov_b32_e32 v136, v222
	v_mov_b32_e32 v137, v223
	v_mov_b32_e32 v138, v224
	v_mov_b32_e32 v139, v225
	global_load_dwordx4 v[218:221], v[254:255], off nt
	global_load_dwordx4 v[222:225], v[254:255], off offset:256 nt
	v_lshl_add_u64 v[254:255], v[254:255], 0, s[80:81]
	v_or_b32_e32 v140, 32, v176
	v_ashrrev_i32_e32 v141, 31, v140
	v_lshlrev_b64 v[140:141], 11, v[140:141]
	v_lshl_add_u64 v[140:141], s[16:17], 0, v[140:141]
	v_lshl_add_u64 v[140:141], v[140:141], 0, v[130:131]
	v_lshlrev_b32_e32 v142, 16, v132
	v_and_b32_e32 v143, 0xffff0000, v132
	v_lshlrev_b32_e32 v132, 16, v133
	v_and_b32_e32 v133, 0xffff0000, v133
	v_lshlrev_b32_e32 v144, 16, v134
	v_and_b32_e32 v145, 0xffff0000, v134
	v_lshlrev_b32_e32 v134, 16, v135
	v_and_b32_e32 v135, 0xffff0000, v135
	v_lshlrev_b32_e32 v146, 16, v136
	v_and_b32_e32 v147, 0xffff0000, v136
	v_lshlrev_b32_e32 v136, 16, v137
	v_and_b32_e32 v137, 0xffff0000, v137
	v_lshlrev_b32_e32 v148, 16, v138
	v_and_b32_e32 v149, 0xffff0000, v138
	v_lshlrev_b32_e32 v138, 16, v139
	v_and_b32_e32 v139, 0xffff0000, v139
	v_pk_fma_f32 v[90:91], v[132:133], s[36:37], v[90:91] op_sel_hi:[1,0,1]
	v_pk_fma_f32 v[88:89], v[142:143], s[36:37], v[88:89] op_sel_hi:[1,0,1]
	v_pk_fma_f32 v[58:59], v[134:135], s[36:37], v[58:59] op_sel_hi:[1,0,1]
	v_pk_fma_f32 v[56:57], v[144:145], s[36:37], v[56:57] op_sel_hi:[1,0,1]
	v_pk_fma_f32 v[54:55], v[136:137], s[36:37], v[54:55] op_sel_hi:[1,0,1]
	v_pk_fma_f32 v[52:53], v[146:147], s[36:37], v[52:53] op_sel_hi:[1,0,1]
	v_pk_fma_f32 v[50:51], v[138:139], s[36:37], v[50:51] op_sel_hi:[1,0,1]
	v_pk_fma_f32 v[48:49], v[148:149], s[36:37], v[48:49] op_sel_hi:[1,0,1]
	s_nop 0
	s_waitcnt vmcnt(8)
	v_permlane16_swap_b32_e32 v226, v228
	v_permlane16_swap_b32_e32 v227, v229
	v_permlane16_swap_b32_e32 v230, v232
	v_permlane16_swap_b32_e32 v231, v233
	v_permlane32_swap_b32_e32 v226, v228
	v_permlane32_swap_b32_e32 v227, v229
	v_permlane32_swap_b32_e32 v230, v232
	v_permlane32_swap_b32_e32 v231, v233
	v_mov_b32_e32 v132, v226
	v_mov_b32_e32 v133, v227
	v_mov_b32_e32 v134, v228
	v_mov_b32_e32 v135, v229
	v_mov_b32_e32 v136, v230
	v_mov_b32_e32 v137, v231
	v_mov_b32_e32 v138, v232
	v_mov_b32_e32 v139, v233
	global_load_dwordx4 v[226:229], v[254:255], off nt
	global_load_dwordx4 v[230:233], v[254:255], off offset:256 nt
	v_or_b32_e32 v140, 48, v176
	v_ashrrev_i32_e32 v141, 31, v140
	v_lshlrev_b64 v[140:141], 11, v[140:141]
	v_lshl_add_u64 v[140:141], s[16:17], 0, v[140:141]
	v_lshl_add_u64 v[140:141], v[140:141], 0, v[130:131]
	v_lshlrev_b32_e32 v142, 16, v132
	v_and_b32_e32 v143, 0xffff0000, v132
	v_lshlrev_b32_e32 v132, 16, v133
	v_and_b32_e32 v133, 0xffff0000, v133
	v_lshlrev_b32_e32 v144, 16, v134
	v_and_b32_e32 v145, 0xffff0000, v134
	v_lshlrev_b32_e32 v134, 16, v135
	v_and_b32_e32 v135, 0xffff0000, v135
	v_lshlrev_b32_e32 v146, 16, v136
	v_and_b32_e32 v147, 0xffff0000, v136
	v_lshlrev_b32_e32 v136, 16, v137
	v_and_b32_e32 v137, 0xffff0000, v137
	v_lshlrev_b32_e32 v148, 16, v138
	v_and_b32_e32 v149, 0xffff0000, v138
	v_lshlrev_b32_e32 v138, 16, v139
	v_and_b32_e32 v139, 0xffff0000, v139
	v_pk_fma_f32 v[98:99], v[132:133], s[36:37], v[98:99] op_sel_hi:[1,0,1]
	v_pk_fma_f32 v[96:97], v[142:143], s[36:37], v[96:97] op_sel_hi:[1,0,1]
	v_pk_fma_f32 v[82:83], v[134:135], s[36:37], v[82:83] op_sel_hi:[1,0,1]
	v_pk_fma_f32 v[80:81], v[144:145], s[36:37], v[80:81] op_sel_hi:[1,0,1]
	v_pk_fma_f32 v[78:79], v[136:137], s[36:37], v[78:79] op_sel_hi:[1,0,1]
	v_pk_fma_f32 v[76:77], v[146:147], s[36:37], v[76:77] op_sel_hi:[1,0,1]
	v_pk_fma_f32 v[70:71], v[138:139], s[36:37], v[70:71] op_sel_hi:[1,0,1]
	v_pk_fma_f32 v[68:69], v[148:149], s[36:37], v[68:69] op_sel_hi:[1,0,1]
	s_nop 0
	s_waitcnt vmcnt(8)
	v_permlane16_swap_b32_e32 v234, v236
	v_permlane16_swap_b32_e32 v235, v237
	v_permlane16_swap_b32_e32 v238, v240
	v_permlane16_swap_b32_e32 v239, v241
	v_permlane32_swap_b32_e32 v234, v236
	v_permlane32_swap_b32_e32 v235, v237
	v_permlane32_swap_b32_e32 v238, v240
	v_permlane32_swap_b32_e32 v239, v241
	v_mov_b32_e32 v132, v234
	v_mov_b32_e32 v133, v235
	v_mov_b32_e32 v134, v236
	v_mov_b32_e32 v135, v237
	v_mov_b32_e32 v136, v238
	v_mov_b32_e32 v137, v239
	v_mov_b32_e32 v138, v240
	v_mov_b32_e32 v139, v241
	v_add_u32_e32 v140, 0x80, v176
	v_ashrrev_i32_e32 v141, 31, v140
	v_lshlrev_b64 v[140:141], 11, v[140:141]
	v_lshl_add_u64 v[140:141], s[16:17], 0, v[140:141]
	v_lshl_add_u64 v[140:141], v[140:141], 0, v[130:131]
	v_lshlrev_b32_e32 v142, 16, v132
	v_and_b32_e32 v143, 0xffff0000, v132
	v_lshlrev_b32_e32 v132, 16, v133
	v_and_b32_e32 v133, 0xffff0000, v133
	v_lshlrev_b32_e32 v144, 16, v134
	v_and_b32_e32 v145, 0xffff0000, v134
	v_lshlrev_b32_e32 v134, 16, v135
	v_and_b32_e32 v135, 0xffff0000, v135
	v_lshlrev_b32_e32 v146, 16, v136
	v_and_b32_e32 v147, 0xffff0000, v136
	v_lshlrev_b32_e32 v136, 16, v137
	v_and_b32_e32 v137, 0xffff0000, v137
	v_lshlrev_b32_e32 v148, 16, v138
	v_and_b32_e32 v149, 0xffff0000, v138
	v_lshlrev_b32_e32 v138, 16, v139
	v_and_b32_e32 v139, 0xffff0000, v139
	v_pk_fma_f32 v[122:123], v[132:133], s[36:37], v[122:123] op_sel_hi:[1,0,1]
	v_pk_fma_f32 v[120:121], v[142:143], s[36:37], v[120:121] op_sel_hi:[1,0,1]
	v_pk_fma_f32 v[114:115], v[134:135], s[36:37], v[114:115] op_sel_hi:[1,0,1]
	v_pk_fma_f32 v[112:113], v[144:145], s[36:37], v[112:113] op_sel_hi:[1,0,1]
	v_pk_fma_f32 v[106:107], v[136:137], s[36:37], v[106:107] op_sel_hi:[1,0,1]
	v_pk_fma_f32 v[104:105], v[146:147], s[36:37], v[104:105] op_sel_hi:[1,0,1]
	v_pk_fma_f32 v[86:87], v[138:139], s[36:37], v[86:87] op_sel_hi:[1,0,1]
	v_pk_fma_f32 v[84:85], v[148:149], s[36:37], v[84:85] op_sel_hi:[1,0,1]
	s_nop 0
	s_waitcnt vmcnt(6)
	v_permlane16_swap_b32_e32 v242, v244
	v_permlane16_swap_b32_e32 v243, v245
	v_permlane16_swap_b32_e32 v246, v248
	v_permlane16_swap_b32_e32 v247, v249
	v_permlane32_swap_b32_e32 v242, v244
	v_permlane32_swap_b32_e32 v243, v245
	v_permlane32_swap_b32_e32 v246, v248
	v_permlane32_swap_b32_e32 v247, v249
	v_mov_b32_e32 v132, v242
	v_mov_b32_e32 v133, v243
	v_mov_b32_e32 v134, v244
	v_mov_b32_e32 v135, v245
	v_mov_b32_e32 v136, v246
	v_mov_b32_e32 v137, v247
	v_mov_b32_e32 v138, v248
	v_mov_b32_e32 v139, v249
	v_add_u32_e32 v140, 0x90, v176
	v_ashrrev_i32_e32 v141, 31, v140
	v_lshlrev_b64 v[140:141], 11, v[140:141]
	v_lshl_add_u64 v[140:141], s[16:17], 0, v[140:141]
	v_lshl_add_u64 v[140:141], v[140:141], 0, v[130:131]
	v_lshlrev_b32_e32 v142, 16, v132
	v_and_b32_e32 v143, 0xffff0000, v132
	v_lshlrev_b32_e32 v132, 16, v133
	v_and_b32_e32 v133, 0xffff0000, v133
	v_lshlrev_b32_e32 v144, 16, v134
	v_and_b32_e32 v145, 0xffff0000, v134
	v_lshlrev_b32_e32 v134, 16, v135
	v_and_b32_e32 v135, 0xffff0000, v135
	v_lshlrev_b32_e32 v146, 16, v136
	v_and_b32_e32 v147, 0xffff0000, v136
	v_lshlrev_b32_e32 v136, 16, v137
	v_and_b32_e32 v137, 0xffff0000, v137
	v_lshlrev_b32_e32 v148, 16, v138
	v_and_b32_e32 v149, 0xffff0000, v138
	v_lshlrev_b32_e32 v138, 16, v139
	v_and_b32_e32 v139, 0xffff0000, v139
	v_pk_fma_f32 v[14:15], v[132:133], s[36:37], v[14:15] op_sel_hi:[1,0,1]
	v_pk_fma_f32 v[12:13], v[142:143], s[36:37], v[12:13] op_sel_hi:[1,0,1]
	v_pk_fma_f32 v[10:11], v[134:135], s[36:37], v[10:11] op_sel_hi:[1,0,1]
	v_pk_fma_f32 v[8:9], v[144:145], s[36:37], v[8:9] op_sel_hi:[1,0,1]
	v_pk_fma_f32 v[6:7], v[136:137], s[36:37], v[6:7] op_sel_hi:[1,0,1]
	v_pk_fma_f32 v[4:5], v[146:147], s[36:37], v[4:5] op_sel_hi:[1,0,1]
	v_pk_fma_f32 v[2:3], v[138:139], s[36:37], v[2:3] op_sel_hi:[1,0,1]
	v_pk_fma_f32 v[0:1], v[148:149], s[36:37], v[0:1] op_sel_hi:[1,0,1]
	s_nop 0
	s_waitcnt vmcnt(4)
	v_permlane16_swap_b32_e32 v210, v212
	v_permlane16_swap_b32_e32 v211, v213
	v_permlane16_swap_b32_e32 v214, v216
	v_permlane16_swap_b32_e32 v215, v217
	v_permlane32_swap_b32_e32 v210, v212
	v_permlane32_swap_b32_e32 v211, v213
	v_permlane32_swap_b32_e32 v214, v216
	v_permlane32_swap_b32_e32 v215, v217
	v_mov_b32_e32 v132, v210
	v_mov_b32_e32 v133, v211
	v_mov_b32_e32 v134, v212
	v_mov_b32_e32 v135, v213
	v_mov_b32_e32 v136, v214
	v_mov_b32_e32 v137, v215
	v_mov_b32_e32 v138, v216
	v_mov_b32_e32 v139, v217
	v_add_u32_e32 v140, 0xa0, v176
	v_ashrrev_i32_e32 v141, 31, v140
	v_lshlrev_b64 v[140:141], 11, v[140:141]
	v_lshl_add_u64 v[140:141], s[16:17], 0, v[140:141]
	v_lshl_add_u64 v[140:141], v[140:141], 0, v[130:131]
	v_lshlrev_b32_e32 v142, 16, v132
	v_and_b32_e32 v143, 0xffff0000, v132
	v_lshlrev_b32_e32 v132, 16, v133
	v_and_b32_e32 v133, 0xffff0000, v133
	v_lshlrev_b32_e32 v144, 16, v134
	v_and_b32_e32 v145, 0xffff0000, v134
	v_lshlrev_b32_e32 v134, 16, v135
	v_and_b32_e32 v135, 0xffff0000, v135
	v_lshlrev_b32_e32 v146, 16, v136
	v_and_b32_e32 v147, 0xffff0000, v136
	v_lshlrev_b32_e32 v136, 16, v137
	v_and_b32_e32 v137, 0xffff0000, v137
	v_lshlrev_b32_e32 v148, 16, v138
	v_and_b32_e32 v149, 0xffff0000, v138
	v_lshlrev_b32_e32 v138, 16, v139
	v_and_b32_e32 v139, 0xffff0000, v139
	v_pk_fma_f32 v[30:31], v[132:133], s[36:37], v[30:31] op_sel_hi:[1,0,1]
	v_pk_fma_f32 v[28:29], v[142:143], s[36:37], v[28:29] op_sel_hi:[1,0,1]
	v_pk_fma_f32 v[26:27], v[134:135], s[36:37], v[26:27] op_sel_hi:[1,0,1]
	v_pk_fma_f32 v[24:25], v[144:145], s[36:37], v[24:25] op_sel_hi:[1,0,1]
	v_pk_fma_f32 v[22:23], v[136:137], s[36:37], v[22:23] op_sel_hi:[1,0,1]
	v_pk_fma_f32 v[20:21], v[146:147], s[36:37], v[20:21] op_sel_hi:[1,0,1]
	v_pk_fma_f32 v[18:19], v[138:139], s[36:37], v[18:19] op_sel_hi:[1,0,1]
	v_pk_fma_f32 v[16:17], v[148:149], s[36:37], v[16:17] op_sel_hi:[1,0,1]
	v_add_u32_e32 v142, 0xb0, v176
	s_waitcnt vmcnt(2)
	v_permlane16_swap_b32_e32 v218, v220
	v_permlane16_swap_b32_e32 v219, v221
	v_permlane16_swap_b32_e32 v222, v224
	v_permlane16_swap_b32_e32 v223, v225
	v_permlane32_swap_b32_e32 v218, v220
	v_permlane32_swap_b32_e32 v219, v221
	v_permlane32_swap_b32_e32 v222, v224
	v_permlane32_swap_b32_e32 v223, v225
	v_mov_b32_e32 v134, v218
	v_mov_b32_e32 v135, v219
	v_mov_b32_e32 v136, v220
	v_mov_b32_e32 v137, v221
	v_mov_b32_e32 v138, v222
	v_mov_b32_e32 v139, v223
	v_mov_b32_e32 v140, v224
	v_mov_b32_e32 v141, v225
	v_ashrrev_i32_e32 v143, 31, v142
	v_lshlrev_b64 v[142:143], 11, v[142:143]
	v_lshl_add_u64 v[142:143], s[16:17], 0, v[142:143]
	v_lshl_add_u64 v[130:131], v[142:143], 0, v[130:131]
	v_mov_b32_e32 v142, v45
	v_mov_b32_e32 v143, v46
	v_mov_b32_e32 v144, v44
	v_mov_b32_e32 v145, v47
	v_pk_add_f32 v[142:143], v[142:143], v[144:145]
	v_mov_b32_e32 v146, v41
	v_mov_b32_e32 v147, v42
	v_and_b32_e32 v133, 64, v203
	v_xor_b32_e32 v132, 16, v203
	v_add_u32_e32 v133, 64, v133
	v_cmp_lt_i32_e32 vcc, v132, v133
	v_lshlrev_b32_e32 v148, 16, v134
	v_and_b32_e32 v149, 0xffff0000, v134
	v_lshlrev_b32_e32 v134, 16, v135
	v_and_b32_e32 v135, 0xffff0000, v135
	v_lshlrev_b32_e32 v150, 16, v136
	v_and_b32_e32 v151, 0xffff0000, v136
	v_lshlrev_b32_e32 v136, 16, v137
	v_and_b32_e32 v137, 0xffff0000, v137
	v_lshlrev_b32_e32 v152, 16, v138
	v_and_b32_e32 v153, 0xffff0000, v138
	v_lshlrev_b32_e32 v138, 16, v139
	v_and_b32_e32 v139, 0xffff0000, v139
	v_lshlrev_b32_e32 v154, 16, v140
	v_and_b32_e32 v155, 0xffff0000, v140
	v_lshlrev_b32_e32 v140, 16, v141
	v_and_b32_e32 v141, 0xffff0000, v141
	v_pk_fma_f32 v[94:95], v[134:135], s[36:37], v[94:95] op_sel_hi:[1,0,1]
	v_pk_fma_f32 v[92:93], v[148:149], s[36:37], v[92:93] op_sel_hi:[1,0,1]
	v_pk_fma_f32 v[74:75], v[136:137], s[36:37], v[74:75] op_sel_hi:[1,0,1]
	v_pk_fma_f32 v[72:73], v[150:151], s[36:37], v[72:73] op_sel_hi:[1,0,1]
	v_pk_fma_f32 v[66:67], v[138:139], s[36:37], v[66:67] op_sel_hi:[1,0,1]
	v_pk_fma_f32 v[64:65], v[152:153], s[36:37], v[64:65] op_sel_hi:[1,0,1]
	v_pk_fma_f32 v[62:63], v[140:141], s[36:37], v[62:63] op_sel_hi:[1,0,1]
	v_pk_fma_f32 v[60:61], v[154:155], s[36:37], v[60:61] op_sel_hi:[1,0,1]
	v_mov_b32_e32 v134, v40
	v_mov_b32_e32 v135, v43
	v_add_f32_e32 v141, v36, v37
	v_add_f32_e32 v149, v38, v39
	v_mov_b32_e32 v140, v32
	v_mov_b32_e32 v148, v33
	v_pk_add_f32 v[130:131], v[146:147], v[134:135]
	v_pk_add_f32 v[134:135], v[140:141], v[148:149]
	v_add_f32_e32 v140, v142, v143
	v_pk_add_f32 v[130:131], v[130:131], v[130:131] op_sel_hi:[0,1]
	v_mov_b32_e32 v152, v35
	v_add_f32_e32 v153, 0, v140
	v_mov_b32_e32 v130, v34
	v_pk_add_f32 v[130:131], v[130:131], v[152:153]
	v_cndmask_b32_e32 v132, v203, v132, vcc
	v_pk_add_f32 v[130:131], v[134:135], v[130:131]
	v_lshlrev_b32_e32 v132, 2, v132
	v_add_f32_e32 v131, v130, v131
	v_mov_b32_e32 v134, v131
	s_nop 1
	v_permlane16_swap_b32_e32 v134, v131
	s_nop 1
	v_xor_b32_e32 v130, 32, v203
	v_cmp_lt_i32_e32 vcc, v130, v133
	s_waitcnt lgkmcnt(0)
	v_add_f32_e32 v131, v131, v134
	v_cndmask_b32_e32 v130, v203, v130, vcc
	v_lshlrev_b32_e32 v130, 2, v130
	v_mov_b32_e32 v133, v131
	s_nop 1
	v_permlane32_swap_b32_e32 v133, v131
	s_nop 1
	s_waitcnt lgkmcnt(0)
	v_add_f32_e32 v131, v131, v133
	v_fmamk_f32 v134, v131, 0xbc800000, v47
	v_fmamk_f32 v140, v131, 0xbc800000, v45
	v_fmamk_f32 v142, v131, 0xbc800000, v43
	v_fmamk_f32 v146, v131, 0xbc800000, v41
	v_fmamk_f32 v133, v131, 0xbc800000, v46
	v_fmamk_f32 v135, v131, 0xbc800000, v44
	v_fmamk_f32 v141, v131, 0xbc800000, v42
	v_fmamk_f32 v143, v131, 0xbc800000, v40
	v_fmamk_f32 v148, v131, 0xbc800000, v39
	v_fmamk_f32 v152, v131, 0xbc800000, v37
	v_mul_f32_e32 v140, v140, v140
	v_mul_f32_e32 v134, v134, v134
	v_mul_f32_e32 v146, v146, v146
	v_mul_f32_e32 v142, v142, v142
	v_fmamk_f32 v147, v131, 0xbc800000, v38
	v_fmamk_f32 v149, v131, 0xbc800000, v36
	v_fmamk_f32 v154, v131, 0xbc800000, v35
	v_fmamk_f32 v156, v131, 0xbc800000, v33
	v_mul_f32_e32 v152, v152, v152
	v_mul_f32_e32 v148, v148, v148
	v_fmac_f32_e32 v140, v135, v135
	v_fmac_f32_e32 v134, v133, v133
	v_fmac_f32_e32 v146, v143, v143
	v_fmac_f32_e32 v142, v141, v141
	v_fmamk_f32 v153, v131, 0xbc800000, v34
	v_fmamk_f32 v155, v131, 0xbc800000, v32
	v_mul_f32_e32 v156, v156, v156
	v_mul_f32_e32 v154, v154, v154
	v_fmac_f32_e32 v152, v149, v149
	v_fmac_f32_e32 v148, v147, v147
	v_add_f32_e32 v133, v140, v134
	v_add_f32_e32 v134, v146, v142
	v_fmac_f32_e32 v156, v155, v155
	v_fmac_f32_e32 v154, v153, v153
	v_add_f32_e32 v135, v152, v148
	v_add_f32_e32 v133, v133, v134
	v_add_f32_e32 v140, v156, v154
	v_add_f32_e32 v133, v135, v133
	v_add_f32_e32 v133, v140, v133
	v_mov_b32_e32 v134, v133
	s_nop 1
	v_permlane16_swap_b32_e32 v134, v133
	s_nop 1
	s_waitcnt lgkmcnt(0)
	v_add_f32_e32 v133, v133, v134
	v_mov_b32_e32 v134, v133
	s_nop 1
	v_permlane32_swap_b32_e32 v134, v133
	s_nop 1
	s_waitcnt vmcnt(0)
	v_permlane16_swap_b32_e32 v226, v228
	v_permlane16_swap_b32_e32 v227, v229
	v_permlane16_swap_b32_e32 v230, v232
	v_permlane16_swap_b32_e32 v231, v233
	v_permlane32_swap_b32_e32 v226, v228
	v_permlane32_swap_b32_e32 v227, v229
	v_permlane32_swap_b32_e32 v230, v232
	v_permlane32_swap_b32_e32 v231, v233
	v_mov_b32_e32 v136, v226
	v_mov_b32_e32 v137, v227
	v_mov_b32_e32 v138, v228
	v_mov_b32_e32 v139, v229
	v_mov_b32_e32 v150, v230
	v_mov_b32_e32 v151, v231
	v_mov_b32_e32 v144, v232
	v_mov_b32_e32 v145, v233
	v_lshlrev_b32_e32 v140, 16, v136
	v_and_b32_e32 v141, 0xffff0000, v136
	v_lshlrev_b32_e32 v136, 16, v137
	v_and_b32_e32 v137, 0xffff0000, v137
	v_lshlrev_b32_e32 v142, 16, v138
	v_and_b32_e32 v143, 0xffff0000, v138
	v_lshlrev_b32_e32 v138, 16, v139
	v_and_b32_e32 v139, 0xffff0000, v139
	v_lshlrev_b32_e32 v146, 16, v150
	v_and_b32_e32 v147, 0xffff0000, v150
	v_lshlrev_b32_e32 v148, 16, v151
	v_and_b32_e32 v149, 0xffff0000, v151
	v_lshlrev_b32_e32 v150, 16, v144
	v_and_b32_e32 v151, 0xffff0000, v144
	v_lshlrev_b32_e32 v144, 16, v145
	v_and_b32_e32 v145, 0xffff0000, v145
	v_pk_fma_f32 v[126:127], v[136:137], s[36:37], v[126:127] op_sel_hi:[1,0,1]
	v_pk_fma_f32 v[124:125], v[140:141], s[36:37], v[124:125] op_sel_hi:[1,0,1]
	v_pk_fma_f32 v[118:119], v[138:139], s[36:37], v[118:119] op_sel_hi:[1,0,1]
	v_pk_fma_f32 v[116:117], v[142:143], s[36:37], v[116:117] op_sel_hi:[1,0,1]
	v_pk_fma_f32 v[110:111], v[148:149], s[36:37], v[110:111] op_sel_hi:[1,0,1]
	v_pk_fma_f32 v[108:109], v[146:147], s[36:37], v[108:109] op_sel_hi:[1,0,1]
	v_pk_fma_f32 v[102:103], v[144:145], s[36:37], v[102:103] op_sel_hi:[1,0,1]
	v_pk_fma_f32 v[100:101], v[150:151], s[36:37], v[100:101] op_sel_hi:[1,0,1]
	s_nop 0
	s_and_saveexec_b64 s[48:49], s[12:13]
	s_cbranch_execz .LBB0_393
	v_mul_f32_e32 v136, 0x3c800000, v131
	s_waitcnt lgkmcnt(0)
	v_add_f32_e32 v137, v133, v134
	ds_write_b64 v208, v[136:137]
.LBB0_393:
	s_or_b64 exec, exec, s[48:49]
	s_waitcnt lgkmcnt(0)
	v_pk_add_f32 v[132:133], v[48:49], v[50:51]
	v_pk_add_f32 v[134:135], v[52:53], v[54:55]
	v_pk_add_f32 v[136:137], v[56:57], v[58:59]
	v_pk_add_f32 v[138:139], v[88:89], v[90:91]
	v_pk_add_f32 v[132:133], v[132:133], v[134:135]
	v_pk_add_f32 v[136:137], v[136:137], v[138:139]
	s_nop 0
	v_pk_add_f32 v[132:133], v[132:133], v[136:137]
	s_nop 0
	v_add_f32_e32 v131, v132, v133
	v_mov_b32_e32 v133, v131
	s_nop 1
	v_permlane16_swap_b32_e32 v133, v131
	s_nop 1
	v_add_f32_e32 v131, v131, v133
	v_mov_b32_e32 v133, v131
	s_nop 1
	v_permlane32_swap_b32_e32 v133, v131
	s_nop 1
	v_add_f32_e32 v131, v131, v133
	v_pk_fma_f32 v[132:133], v[130:131], s[96:97], v[48:49] op_sel:[1,0,0] op_sel_hi:[1,0,1]
	v_pk_fma_f32 v[134:135], v[130:131], s[96:97], v[50:51] op_sel:[1,0,0] op_sel_hi:[1,0,1]
	v_pk_fma_f32 v[136:137], v[130:131], s[96:97], v[52:53] op_sel:[1,0,0] op_sel_hi:[1,0,1]
	v_pk_fma_f32 v[138:139], v[130:131], s[96:97], v[54:55] op_sel:[1,0,0] op_sel_hi:[1,0,1]
	v_pk_fma_f32 v[140:141], v[130:131], s[96:97], v[56:57] op_sel:[1,0,0] op_sel_hi:[1,0,1]
	v_pk_fma_f32 v[142:143], v[130:131], s[96:97], v[58:59] op_sel:[1,0,0] op_sel_hi:[1,0,1]
	v_pk_fma_f32 v[144:145], v[130:131], s[96:97], v[88:89] op_sel:[1,0,0] op_sel_hi:[1,0,1]
	v_pk_fma_f32 v[146:147], v[130:131], s[96:97], v[90:91] op_sel:[1,0,0] op_sel_hi:[1,0,1]
	v_pk_mul_f32 v[132:133], v[132:133], v[132:133]
	v_pk_mul_f32 v[134:135], v[134:135], v[134:135]
	v_pk_fma_f32 v[132:133], v[136:137], v[136:137], v[132:133]
	v_pk_fma_f32 v[134:135], v[138:139], v[138:139], v[134:135]
	v_pk_fma_f32 v[132:133], v[140:141], v[140:141], v[132:133]
	v_pk_fma_f32 v[134:135], v[142:143], v[142:143], v[134:135]
	v_pk_fma_f32 v[132:133], v[144:145], v[144:145], v[132:133]
	v_pk_fma_f32 v[134:135], v[146:147], v[146:147], v[134:135]
	v_pk_add_f32 v[132:133], v[132:133], v[134:135]
	s_nop 0
	v_add_f32_e32 v133, v132, v133
	v_mov_b32_e32 v134, v133
	s_nop 1
	v_permlane16_swap_b32_e32 v134, v133
	s_nop 1
	v_add_f32_e32 v133, v133, v134
	v_mov_b32_e32 v134, v133
	s_nop 1
	v_permlane32_swap_b32_e32 v134, v133
	s_nop 1
	s_and_saveexec_b64 s[48:49], s[12:13]
	s_cbranch_execz .LBB0_395
	v_mul_f32_e32 v136, 0x3c800000, v131
	s_waitcnt lgkmcnt(0)
	v_add_f32_e32 v137, v133, v134
	ds_write_b64 v208, v[136:137] offset:512
.LBB0_395:
	s_or_b64 exec, exec, s[48:49]
	s_waitcnt lgkmcnt(0)
	v_pk_add_f32 v[132:133], v[68:69], v[70:71]
	v_pk_add_f32 v[134:135], v[76:77], v[78:79]
	v_pk_add_f32 v[136:137], v[80:81], v[82:83]
	v_pk_add_f32 v[138:139], v[96:97], v[98:99]
	v_pk_add_f32 v[132:133], v[132:133], v[134:135]
	v_pk_add_f32 v[136:137], v[136:137], v[138:139]
	s_nop 0
	v_pk_add_f32 v[132:133], v[132:133], v[136:137]
	s_nop 0
	v_add_f32_e32 v131, v132, v133
	v_mov_b32_e32 v133, v131
	s_nop 1
	v_permlane16_swap_b32_e32 v133, v131
	s_nop 1
	v_add_f32_e32 v131, v131, v133
	v_mov_b32_e32 v133, v131
	s_nop 1
	v_permlane32_swap_b32_e32 v133, v131
	s_nop 1
	v_add_f32_e32 v131, v131, v133
	v_pk_fma_f32 v[132:133], v[130:131], s[96:97], v[68:69] op_sel:[1,0,0] op_sel_hi:[1,0,1]
	v_pk_fma_f32 v[134:135], v[130:131], s[96:97], v[70:71] op_sel:[1,0,0] op_sel_hi:[1,0,1]
	v_pk_fma_f32 v[136:137], v[130:131], s[96:97], v[76:77] op_sel:[1,0,0] op_sel_hi:[1,0,1]
	v_pk_fma_f32 v[138:139], v[130:131], s[96:97], v[78:79] op_sel:[1,0,0] op_sel_hi:[1,0,1]
	v_pk_fma_f32 v[140:141], v[130:131], s[96:97], v[80:81] op_sel:[1,0,0] op_sel_hi:[1,0,1]
	v_pk_fma_f32 v[142:143], v[130:131], s[96:97], v[82:83] op_sel:[1,0,0] op_sel_hi:[1,0,1]
	v_pk_fma_f32 v[144:145], v[130:131], s[96:97], v[96:97] op_sel:[1,0,0] op_sel_hi:[1,0,1]
	v_pk_fma_f32 v[146:147], v[130:131], s[96:97], v[98:99] op_sel:[1,0,0] op_sel_hi:[1,0,1]
	v_pk_mul_f32 v[132:133], v[132:133], v[132:133]
	v_pk_mul_f32 v[134:135], v[134:135], v[134:135]
	v_pk_fma_f32 v[132:133], v[136:137], v[136:137], v[132:133]
	v_pk_fma_f32 v[134:135], v[138:139], v[138:139], v[134:135]
	v_pk_fma_f32 v[132:133], v[140:141], v[140:141], v[132:133]
	v_pk_fma_f32 v[134:135], v[142:143], v[142:143], v[134:135]
	v_pk_fma_f32 v[132:133], v[144:145], v[144:145], v[132:133]
	v_pk_fma_f32 v[134:135], v[146:147], v[146:147], v[134:135]
	v_pk_add_f32 v[132:133], v[132:133], v[134:135]
	s_nop 0
	v_add_f32_e32 v133, v132, v133
	v_mov_b32_e32 v134, v133
	s_nop 1
	v_permlane16_swap_b32_e32 v134, v133
	s_nop 1
	v_add_f32_e32 v133, v133, v134
	v_mov_b32_e32 v134, v133
	s_nop 1
	v_permlane32_swap_b32_e32 v134, v133
	s_nop 1
	s_and_saveexec_b64 s[48:49], s[12:13]
	s_cbranch_execz .LBB0_397
	v_mul_f32_e32 v136, 0x3c800000, v131
	s_waitcnt lgkmcnt(0)
	v_add_f32_e32 v137, v133, v134
	ds_write_b64 v208, v[136:137] offset:1024
.LBB0_397:
	s_or_b64 exec, exec, s[48:49]
	s_waitcnt lgkmcnt(0)
	v_pk_add_f32 v[132:133], v[84:85], v[86:87]
	v_pk_add_f32 v[134:135], v[104:105], v[106:107]
	v_pk_add_f32 v[136:137], v[112:113], v[114:115]
	v_pk_add_f32 v[138:139], v[120:121], v[122:123]
	v_pk_add_f32 v[132:133], v[132:133], v[134:135]
	v_pk_add_f32 v[136:137], v[136:137], v[138:139]
	s_nop 0
	v_pk_add_f32 v[132:133], v[132:133], v[136:137]
	s_nop 0
	v_add_f32_e32 v131, v132, v133
	v_mov_b32_e32 v133, v131
	s_nop 1
	v_permlane16_swap_b32_e32 v133, v131
	s_nop 1
	v_add_f32_e32 v131, v131, v133
	v_mov_b32_e32 v133, v131
	s_nop 1
	v_permlane32_swap_b32_e32 v133, v131
	s_nop 1
	v_add_f32_e32 v131, v131, v133
	v_pk_fma_f32 v[132:133], v[130:131], s[96:97], v[84:85] op_sel:[1,0,0] op_sel_hi:[1,0,1]
	v_pk_fma_f32 v[134:135], v[130:131], s[96:97], v[86:87] op_sel:[1,0,0] op_sel_hi:[1,0,1]
	v_pk_fma_f32 v[136:137], v[130:131], s[96:97], v[104:105] op_sel:[1,0,0] op_sel_hi:[1,0,1]
	v_pk_fma_f32 v[138:139], v[130:131], s[96:97], v[106:107] op_sel:[1,0,0] op_sel_hi:[1,0,1]
	v_pk_fma_f32 v[140:141], v[130:131], s[96:97], v[112:113] op_sel:[1,0,0] op_sel_hi:[1,0,1]
	v_pk_fma_f32 v[142:143], v[130:131], s[96:97], v[114:115] op_sel:[1,0,0] op_sel_hi:[1,0,1]
	v_pk_fma_f32 v[144:145], v[130:131], s[96:97], v[120:121] op_sel:[1,0,0] op_sel_hi:[1,0,1]
	v_pk_fma_f32 v[146:147], v[130:131], s[96:97], v[122:123] op_sel:[1,0,0] op_sel_hi:[1,0,1]
	v_pk_mul_f32 v[132:133], v[132:133], v[132:133]
	v_pk_mul_f32 v[134:135], v[134:135], v[134:135]
	v_pk_fma_f32 v[132:133], v[136:137], v[136:137], v[132:133]
	v_pk_fma_f32 v[134:135], v[138:139], v[138:139], v[134:135]
	v_pk_fma_f32 v[132:133], v[140:141], v[140:141], v[132:133]
	v_pk_fma_f32 v[134:135], v[142:143], v[142:143], v[134:135]
	v_pk_fma_f32 v[132:133], v[144:145], v[144:145], v[132:133]
	v_pk_fma_f32 v[134:135], v[146:147], v[146:147], v[134:135]
	v_pk_add_f32 v[132:133], v[132:133], v[134:135]
	s_nop 0
	v_add_f32_e32 v133, v132, v133
	v_mov_b32_e32 v134, v133
	s_nop 1
	v_permlane16_swap_b32_e32 v134, v133
	s_nop 1
	v_add_f32_e32 v133, v133, v134
	v_mov_b32_e32 v134, v133
	s_nop 1
	v_permlane32_swap_b32_e32 v134, v133
	s_nop 1
	s_and_saveexec_b64 s[48:49], s[12:13]
	s_cbranch_execz .LBB0_399
	v_mul_f32_e32 v136, 0x3c800000, v131
	s_waitcnt lgkmcnt(0)
	v_add_f32_e32 v137, v133, v134
	ds_write_b64 v208, v[136:137] offset:1536
.LBB0_399:
	s_or_b64 exec, exec, s[48:49]
	s_waitcnt lgkmcnt(0)
	v_pk_add_f32 v[132:133], v[0:1], v[2:3]
	v_pk_add_f32 v[134:135], v[4:5], v[6:7]
	v_pk_add_f32 v[136:137], v[8:9], v[10:11]
	v_pk_add_f32 v[138:139], v[12:13], v[14:15]
	v_pk_add_f32 v[132:133], v[132:133], v[134:135]
	v_pk_add_f32 v[136:137], v[136:137], v[138:139]
	s_nop 0
	v_pk_add_f32 v[132:133], v[132:133], v[136:137]
	s_nop 0
	v_add_f32_e32 v131, v132, v133
	v_mov_b32_e32 v133, v131
	s_nop 1
	v_permlane16_swap_b32_e32 v133, v131
	s_nop 1
	v_add_f32_e32 v131, v131, v133
	v_mov_b32_e32 v133, v131
	s_nop 1
	v_permlane32_swap_b32_e32 v133, v131
	s_nop 1
	v_add_f32_e32 v131, v131, v133
	v_pk_fma_f32 v[132:133], v[130:131], s[96:97], v[0:1] op_sel:[1,0,0] op_sel_hi:[1,0,1]
	v_pk_fma_f32 v[134:135], v[130:131], s[96:97], v[2:3] op_sel:[1,0,0] op_sel_hi:[1,0,1]
	v_pk_fma_f32 v[136:137], v[130:131], s[96:97], v[4:5] op_sel:[1,0,0] op_sel_hi:[1,0,1]
	v_pk_fma_f32 v[138:139], v[130:131], s[96:97], v[6:7] op_sel:[1,0,0] op_sel_hi:[1,0,1]
	v_pk_fma_f32 v[140:141], v[130:131], s[96:97], v[8:9] op_sel:[1,0,0] op_sel_hi:[1,0,1]
	v_pk_fma_f32 v[142:143], v[130:131], s[96:97], v[10:11] op_sel:[1,0,0] op_sel_hi:[1,0,1]
	v_pk_fma_f32 v[144:145], v[130:131], s[96:97], v[12:13] op_sel:[1,0,0] op_sel_hi:[1,0,1]
	v_pk_fma_f32 v[146:147], v[130:131], s[96:97], v[14:15] op_sel:[1,0,0] op_sel_hi:[1,0,1]
	v_pk_mul_f32 v[132:133], v[132:133], v[132:133]
	v_pk_mul_f32 v[134:135], v[134:135], v[134:135]
	v_pk_fma_f32 v[132:133], v[136:137], v[136:137], v[132:133]
	v_pk_fma_f32 v[134:135], v[138:139], v[138:139], v[134:135]
	v_pk_fma_f32 v[132:133], v[140:141], v[140:141], v[132:133]
	v_pk_fma_f32 v[134:135], v[142:143], v[142:143], v[134:135]
	v_pk_fma_f32 v[132:133], v[144:145], v[144:145], v[132:133]
	v_pk_fma_f32 v[134:135], v[146:147], v[146:147], v[134:135]
	v_pk_add_f32 v[132:133], v[132:133], v[134:135]
	s_nop 0
	v_add_f32_e32 v133, v132, v133
	v_mov_b32_e32 v134, v133
	s_nop 1
	v_permlane16_swap_b32_e32 v134, v133
	s_nop 1
	v_add_f32_e32 v133, v133, v134
	v_mov_b32_e32 v134, v133
	s_nop 1
	v_permlane32_swap_b32_e32 v134, v133
	s_nop 1
	s_and_saveexec_b64 s[48:49], s[12:13]
	s_cbranch_execz .LBB0_401
	v_mul_f32_e32 v136, 0x3c800000, v131
	s_waitcnt lgkmcnt(0)
	v_add_f32_e32 v137, v133, v134
	ds_write_b64 v208, v[136:137] offset:4096
.LBB0_401:
	s_or_b64 exec, exec, s[48:49]
	s_waitcnt lgkmcnt(0)
	v_pk_add_f32 v[132:133], v[16:17], v[18:19]
	v_pk_add_f32 v[134:135], v[20:21], v[22:23]
	v_pk_add_f32 v[136:137], v[24:25], v[26:27]
	v_pk_add_f32 v[138:139], v[28:29], v[30:31]
	v_pk_add_f32 v[132:133], v[132:133], v[134:135]
	v_pk_add_f32 v[136:137], v[136:137], v[138:139]
	s_nop 0
	v_pk_add_f32 v[132:133], v[132:133], v[136:137]
	s_nop 0
	v_add_f32_e32 v131, v132, v133
	v_mov_b32_e32 v133, v131
	s_nop 1
	v_permlane16_swap_b32_e32 v133, v131
	s_nop 1
	v_add_f32_e32 v131, v131, v133
	v_mov_b32_e32 v133, v131
	s_nop 1
	v_permlane32_swap_b32_e32 v133, v131
	s_nop 1
	v_add_f32_e32 v131, v131, v133
	v_pk_fma_f32 v[132:133], v[130:131], s[96:97], v[16:17] op_sel:[1,0,0] op_sel_hi:[1,0,1]
	v_pk_fma_f32 v[134:135], v[130:131], s[96:97], v[18:19] op_sel:[1,0,0] op_sel_hi:[1,0,1]
	v_pk_fma_f32 v[136:137], v[130:131], s[96:97], v[20:21] op_sel:[1,0,0] op_sel_hi:[1,0,1]
	v_pk_fma_f32 v[138:139], v[130:131], s[96:97], v[22:23] op_sel:[1,0,0] op_sel_hi:[1,0,1]
	v_pk_fma_f32 v[140:141], v[130:131], s[96:97], v[24:25] op_sel:[1,0,0] op_sel_hi:[1,0,1]
	v_pk_fma_f32 v[142:143], v[130:131], s[96:97], v[26:27] op_sel:[1,0,0] op_sel_hi:[1,0,1]
	v_pk_fma_f32 v[144:145], v[130:131], s[96:97], v[28:29] op_sel:[1,0,0] op_sel_hi:[1,0,1]
	v_pk_fma_f32 v[146:147], v[130:131], s[96:97], v[30:31] op_sel:[1,0,0] op_sel_hi:[1,0,1]
	v_pk_mul_f32 v[132:133], v[132:133], v[132:133]
	v_pk_mul_f32 v[134:135], v[134:135], v[134:135]
	v_pk_fma_f32 v[132:133], v[136:137], v[136:137], v[132:133]
	v_pk_fma_f32 v[134:135], v[138:139], v[138:139], v[134:135]
	v_pk_fma_f32 v[132:133], v[140:141], v[140:141], v[132:133]
	v_pk_fma_f32 v[134:135], v[142:143], v[142:143], v[134:135]
	v_pk_fma_f32 v[132:133], v[144:145], v[144:145], v[132:133]
	v_pk_fma_f32 v[134:135], v[146:147], v[146:147], v[134:135]
	v_pk_add_f32 v[132:133], v[132:133], v[134:135]
	s_nop 0
	v_add_f32_e32 v133, v132, v133
	v_mov_b32_e32 v134, v133
	s_nop 1
	v_permlane16_swap_b32_e32 v134, v133
	s_nop 1
	v_add_f32_e32 v133, v133, v134
	v_mov_b32_e32 v134, v133
	s_nop 1
	v_permlane32_swap_b32_e32 v134, v133
	s_nop 1
	s_and_saveexec_b64 s[48:49], s[12:13]
	s_cbranch_execz .LBB0_403
	v_mul_f32_e32 v136, 0x3c800000, v131
	s_waitcnt lgkmcnt(0)
	v_add_f32_e32 v137, v133, v134
	ds_write_b64 v208, v[136:137] offset:4608
.LBB0_403:
	s_or_b64 exec, exec, s[48:49]
	s_waitcnt lgkmcnt(0)
	v_pk_add_f32 v[132:133], v[60:61], v[62:63]
	v_pk_add_f32 v[134:135], v[64:65], v[66:67]
	v_pk_add_f32 v[136:137], v[72:73], v[74:75]
	v_pk_add_f32 v[138:139], v[92:93], v[94:95]
	v_pk_add_f32 v[132:133], v[132:133], v[134:135]
	v_pk_add_f32 v[136:137], v[136:137], v[138:139]
	s_nop 0
	v_pk_add_f32 v[132:133], v[132:133], v[136:137]
	s_nop 0
	v_add_f32_e32 v131, v132, v133
	v_mov_b32_e32 v133, v131
	s_nop 1
	v_permlane16_swap_b32_e32 v133, v131
	s_nop 1
	v_add_f32_e32 v131, v131, v133
	v_mov_b32_e32 v133, v131
	s_nop 1
	v_permlane32_swap_b32_e32 v133, v131
	s_nop 1
	v_add_f32_e32 v131, v131, v133
	v_pk_fma_f32 v[132:133], v[130:131], s[96:97], v[60:61] op_sel:[1,0,0] op_sel_hi:[1,0,1]
	v_pk_fma_f32 v[134:135], v[130:131], s[96:97], v[62:63] op_sel:[1,0,0] op_sel_hi:[1,0,1]
	v_pk_fma_f32 v[136:137], v[130:131], s[96:97], v[64:65] op_sel:[1,0,0] op_sel_hi:[1,0,1]
	v_pk_fma_f32 v[138:139], v[130:131], s[96:97], v[66:67] op_sel:[1,0,0] op_sel_hi:[1,0,1]
	v_pk_fma_f32 v[140:141], v[130:131], s[96:97], v[72:73] op_sel:[1,0,0] op_sel_hi:[1,0,1]
	v_pk_fma_f32 v[142:143], v[130:131], s[96:97], v[74:75] op_sel:[1,0,0] op_sel_hi:[1,0,1]
	v_pk_fma_f32 v[144:145], v[130:131], s[96:97], v[92:93] op_sel:[1,0,0] op_sel_hi:[1,0,1]
	v_pk_fma_f32 v[146:147], v[130:131], s[96:97], v[94:95] op_sel:[1,0,0] op_sel_hi:[1,0,1]
	v_pk_mul_f32 v[132:133], v[132:133], v[132:133]
	v_pk_mul_f32 v[134:135], v[134:135], v[134:135]
	v_pk_fma_f32 v[132:133], v[136:137], v[136:137], v[132:133]
	v_pk_fma_f32 v[134:135], v[138:139], v[138:139], v[134:135]
	v_pk_fma_f32 v[132:133], v[140:141], v[140:141], v[132:133]
	v_pk_fma_f32 v[134:135], v[142:143], v[142:143], v[134:135]
	v_pk_fma_f32 v[132:133], v[144:145], v[144:145], v[132:133]
	v_pk_fma_f32 v[134:135], v[146:147], v[146:147], v[134:135]
	v_pk_add_f32 v[132:133], v[132:133], v[134:135]
	s_nop 0
	v_add_f32_e32 v133, v132, v133
	v_mov_b32_e32 v134, v133
	s_nop 1
	v_permlane16_swap_b32_e32 v134, v133
	s_nop 1
	v_add_f32_e32 v133, v133, v134
	v_mov_b32_e32 v134, v133
	s_nop 1
	v_permlane32_swap_b32_e32 v134, v133
	s_nop 1
	s_and_saveexec_b64 s[48:49], s[12:13]
	s_cbranch_execz .LBB0_405
	v_mul_f32_e32 v136, 0x3c800000, v131
	s_waitcnt lgkmcnt(0)
	v_add_f32_e32 v137, v133, v134
	ds_write_b64 v208, v[136:137] offset:5120
.LBB0_405:
	s_or_b64 exec, exec, s[48:49]
	s_waitcnt lgkmcnt(0)
	v_pk_add_f32 v[132:133], v[100:101], v[102:103]
	v_pk_add_f32 v[134:135], v[108:109], v[110:111]
	v_pk_add_f32 v[136:137], v[116:117], v[118:119]
	v_pk_add_f32 v[138:139], v[124:125], v[126:127]
	v_pk_add_f32 v[132:133], v[132:133], v[134:135]
	v_pk_add_f32 v[136:137], v[136:137], v[138:139]
	s_nop 0
	v_pk_add_f32 v[132:133], v[132:133], v[136:137]
	s_nop 0
	v_add_f32_e32 v131, v132, v133
	v_mov_b32_e32 v133, v131
	s_nop 1
	v_permlane16_swap_b32_e32 v133, v131
	s_nop 1
	v_add_f32_e32 v131, v131, v133
	v_mov_b32_e32 v133, v131
	s_nop 1
	v_permlane32_swap_b32_e32 v133, v131
	s_nop 1
	v_add_f32_e32 v131, v131, v133
	v_pk_fma_f32 v[132:133], v[130:131], s[96:97], v[100:101] op_sel:[1,0,0] op_sel_hi:[1,0,1]
	v_pk_fma_f32 v[134:135], v[130:131], s[96:97], v[102:103] op_sel:[1,0,0] op_sel_hi:[1,0,1]
	v_pk_fma_f32 v[136:137], v[130:131], s[96:97], v[108:109] op_sel:[1,0,0] op_sel_hi:[1,0,1]
	v_pk_fma_f32 v[138:139], v[130:131], s[96:97], v[110:111] op_sel:[1,0,0] op_sel_hi:[1,0,1]
	v_pk_fma_f32 v[140:141], v[130:131], s[96:97], v[116:117] op_sel:[1,0,0] op_sel_hi:[1,0,1]
	v_pk_fma_f32 v[142:143], v[130:131], s[96:97], v[118:119] op_sel:[1,0,0] op_sel_hi:[1,0,1]
	v_pk_fma_f32 v[144:145], v[130:131], s[96:97], v[124:125] op_sel:[1,0,0] op_sel_hi:[1,0,1]
	v_pk_fma_f32 v[146:147], v[130:131], s[96:97], v[126:127] op_sel:[1,0,0] op_sel_hi:[1,0,1]
	v_pk_mul_f32 v[132:133], v[132:133], v[132:133]
	v_pk_mul_f32 v[134:135], v[134:135], v[134:135]
	v_pk_fma_f32 v[132:133], v[136:137], v[136:137], v[132:133]
	v_pk_fma_f32 v[134:135], v[138:139], v[138:139], v[134:135]
	v_pk_fma_f32 v[132:133], v[140:141], v[140:141], v[132:133]
	v_pk_fma_f32 v[134:135], v[142:143], v[142:143], v[134:135]
	v_pk_fma_f32 v[132:133], v[144:145], v[144:145], v[132:133]
	v_pk_fma_f32 v[134:135], v[146:147], v[146:147], v[134:135]
	v_pk_add_f32 v[132:133], v[132:133], v[134:135]
	s_nop 0
	v_add_f32_e32 v133, v132, v133
	v_mov_b32_e32 v134, v133
	s_nop 1
	v_permlane16_swap_b32_e32 v134, v133
	s_nop 1
	v_add_f32_e32 v133, v133, v134
	v_mov_b32_e32 v132, v133
	v_mov_b32_e32 v130, v132
	s_nop 1
	v_permlane32_swap_b32_e32 v130, v132
	s_nop 1
	s_and_saveexec_b64 s[48:49], s[12:13]
	s_cbranch_execz .LBB0_407
	v_mul_f32_e32 v134, 0x3c800000, v131
	s_waitcnt lgkmcnt(0)
	v_add_f32_e32 v135, v132, v130
	ds_write_b64 v208, v[134:135] offset:5632
